# speedup vs baseline: 1.0053x; 1.0053x over previous
;     ...
;   const int rg = (l15 >> 2) & 3;
;   const int gr = (rg == 0) ? 0 : (rg == 1) ? 2 : (rg == 2) ? 3 : 1;
;   const int aoff_r = (wm * (MS * 16) + l15) * 64 + ((quad ^ gr) << 4);
;   const int boff_r = A_BYTES + (wn * 64 + l15) * 64 + ((quad ^ gr) << 4);
; template <int MS>
; DEV void zero_acc(f32x4 (&acc)[MS][4]) {
; #pragma unroll
;   for (int a = 0; a < MS; ++a)
; #pragma unroll
;     for (int b = 0; b < 4; ++b) acc[a][b] = f32x4{0.f, 0.f, 0.f, 0.f};
.LBB0_208:
	s_mov_b64 s[4:5], 0x4000
	v_lshlrev_b32_e32 v6, 6, v9
	v_lshl_add_u64 v[208:209], v[2:3], 0, s[4:5]
	v_and_b32_e32 v187, 0xffffe3c0, v6
	v_bitop3_b32 v189, v10, v9, 48 bitop3:0x78
	v_and_b32_e32 v238, 0x13c0, v6
	v_lshl_add_u64 v[206:207], v[4:5], 0, s[4:5]
	s_mov_b64 s[4:5], 0
	s_mov_b32 s15, 2
	s_mov_b32 s19, 0
	s_mov_b32 s20, 0
	s_branch .LBB0_210

;     ...
;   for (int kt = 0; kt < nk; ++kt) {
;     if (NST == 4 && kt + 2 < nk) asm volatile("s_waitcnt vmcnt(%0)" ::"n"(2 * NLD) : "memory");
;     else if (kt + 1 < nk) asm volatile("s_waitcnt vmcnt(%0)" ::"n"(NLD) : "memory");
;     else asm volatile("s_waitcnt vmcnt(0)" ::: "memory");
;     __builtin_amdgcn_s_barrier();
;     const char* st = smem + (kt % NST) * STAGE;
;     bf16x8 af[MS], bfr[4];
; #pragma unroll
;     for (int ms = 0; ms < MS; ++ms) af[ms] = *(const bf16x8*)(st + aoff_r + ms * 1024);
; #pragma unroll
;     for (int ns = 0; ns < 4; ++ns) bfr[ns] = *(const bf16x8*)(st + boff_r + ns * 1024);
;     asm volatile("" ::: "memory");
;     if (kt + NST - 1 < nk) ISSUE(kt + NST - 1)
;     __builtin_amdgcn_s_setprio(1);
; #pragma unroll
;     for (int ms = 0; ms < MS; ++ms)
; #pragma unroll
;       for (int ns = 0; ns < 4; ++ns) acc[ms][ns] = __builtin_amdgcn_mfma_f32_16x16x32_bf16(af[ms], bfr[ns], acc[ms][ns], 0, 0, 0);
;     __builtin_amdgcn_s_setprio(0);
.LBB0_214:
	s_cmp_eq_u32 s2, 0
	s_cbranch_scc1 .Lk0_f1
	s_mul_hi_u32 s10, s20, 0xaaaaaaab
	s_lshr_b32 s10, s10, 1
	s_mul_i32 s10, s10, 0x12000
	v_subrev_u32_e32 v130, s10, v187
	v_add_u32_e32 v139, s19, v189
	v_add_u32_e32 v130, v139, v130
	v_subrev_u32_e32 v138, s10, v238
	v_add_u32_e32 v150, v139, v138
	s_barrier
	ds_read_b128 v[138:141], v150 offset:16384
	ds_read_b128 v[142:145], v150 offset:17408
	ds_read_b128 v[146:149], v150 offset:18432
	ds_read_b128 v[150:153], v150 offset:19456
	ds_read_b128 v[174:177], v130
	ds_read_b128 v[170:173], v130 offset:1024
	ds_read_b128 v[166:169], v130 offset:2048
	ds_read_b128 v[162:165], v130 offset:3072
	ds_read_b128 v[158:161], v130 offset:4096
	ds_read_b128 v[154:157], v130 offset:5120
	ds_read_b128 v[134:137], v130 offset:6144
	ds_read_b128 v[130:133], v130 offset:7168
	s_cmp_gt_u32 s2, 29
	s_cbranch_scc1 .LBB0_209
	s_mul_i32 s11, s15, 0xab
	s_bfe_u32 s11, s11, 0x70009
	s_mul_i32 s11, s11, 3
	s_add_i32 s2, s4, 0x4000
	s_sub_i32 s11, s15, s11
	s_and_b32 s2, s2, 0x7c000
	s_and_b32 s11, s11, 0xff
	s_and_b32 s10, s4, 0x2000
	s_mulk_i32 s11, 0x6000
	s_lshl_b32 s2, s2, 1
	s_add_i32 s21, s13, s11
	s_setprio 1
	s_waitcnt lgkmcnt(7)
	v_mfma_f32_16x16x32_bf16 v[126:129], v[174:177], v[138:141], v[126:129]
	v_mfma_f32_16x16x32_bf16 v[122:125], v[174:177], v[142:145], v[122:125]
	v_mfma_f32_16x16x32_bf16 v[118:121], v[174:177], v[146:149], v[118:121]
	v_mfma_f32_16x16x32_bf16 v[114:117], v[174:177], v[150:153], v[114:117]
	v_lshl_add_u64 v[214:215], v[198:199], 0, s[2:3]
	s_waitcnt lgkmcnt(6)
	v_mfma_f32_16x16x32_bf16 v[110:113], v[170:173], v[138:141], v[110:113]
	s_lshl_b32 s10, s10, 1
	v_mfma_f32_16x16x32_bf16 v[106:109], v[170:173], v[142:145], v[106:109]
	s_mov_b32 s11, s3
	v_mfma_f32_16x16x32_bf16 v[102:105], v[170:173], v[146:149], v[102:105]
	v_lshl_add_u64 v[214:215], v[214:215], 0, s[10:11]
	v_mfma_f32_16x16x32_bf16 v[98:101], v[170:173], v[150:153], v[98:101]
	s_mov_b32 m0, s21
	s_waitcnt lgkmcnt(5)
	v_mfma_f32_16x16x32_bf16 v[94:97], v[166:169], v[138:141], v[94:97]
	global_load_lds_dwordx4 v[214:215], off
	v_mfma_f32_16x16x32_bf16 v[90:93], v[166:169], v[142:145], v[90:93]
	v_mfma_f32_16x16x32_bf16 v[86:89], v[166:169], v[146:149], v[86:89]
	v_lshl_add_u64 v[214:215], v[200:201], 0, s[2:3]
	v_mfma_f32_16x16x32_bf16 v[82:85], v[166:169], v[150:153], v[82:85]
	v_lshl_add_u64 v[214:215], v[214:215], 0, s[10:11]
	s_waitcnt lgkmcnt(4)
	v_mfma_f32_16x16x32_bf16 v[78:81], v[162:165], v[138:141], v[78:81]
	s_add_i32 m0, s21, 0x1000
	v_mfma_f32_16x16x32_bf16 v[74:77], v[162:165], v[142:145], v[74:77]
	global_load_lds_dwordx4 v[214:215], off
	v_mfma_f32_16x16x32_bf16 v[70:73], v[162:165], v[146:149], v[70:73]
	v_lshl_add_u64 v[214:215], v[202:203], 0, s[2:3]
	v_mfma_f32_16x16x32_bf16 v[66:69], v[162:165], v[150:153], v[66:69]
	v_lshl_add_u64 v[214:215], v[214:215], 0, s[10:11]
	s_waitcnt lgkmcnt(3)
	v_mfma_f32_16x16x32_bf16 v[62:65], v[158:161], v[138:141], v[62:65]
	v_mfma_f32_16x16x32_bf16 v[58:61], v[158:161], v[142:145], v[58:61]
	s_add_i32 m0, s21, 0x2000
	v_mfma_f32_16x16x32_bf16 v[54:57], v[158:161], v[146:149], v[54:57]
	global_load_lds_dwordx4 v[214:215], off
	v_mfma_f32_16x16x32_bf16 v[50:53], v[158:161], v[150:153], v[50:53]
	v_lshl_add_u64 v[214:215], v[204:205], 0, s[2:3]
	s_waitcnt lgkmcnt(2)
	v_mfma_f32_16x16x32_bf16 v[46:49], v[154:157], v[138:141], v[46:49]
	v_lshl_add_u64 v[214:215], v[214:215], 0, s[10:11]
	v_mfma_f32_16x16x32_bf16 v[42:45], v[154:157], v[142:145], v[42:45]
	s_add_i32 m0, s21, 0x3000
	v_mfma_f32_16x16x32_bf16 v[38:41], v[154:157], v[146:149], v[38:41]
	global_load_lds_dwordx4 v[214:215], off
	v_mfma_f32_16x16x32_bf16 v[34:37], v[154:157], v[150:153], v[34:37]
	s_waitcnt lgkmcnt(1)
	v_mfma_f32_16x16x32_bf16 v[30:33], v[134:137], v[138:141], v[30:33]
	v_lshl_add_u64 v[214:215], v[208:209], 0, s[4:5]
	v_mfma_f32_16x16x32_bf16 v[26:29], v[134:137], v[142:145], v[26:29]
	s_add_i32 m0, s21, 0x4000
	v_mfma_f32_16x16x32_bf16 v[22:25], v[134:137], v[146:149], v[22:25]
	global_load_lds_dwordx4 v[214:215], off
	v_mfma_f32_16x16x32_bf16 v[18:21], v[134:137], v[150:153], v[18:21]
	v_lshl_add_u64 v[214:215], v[206:207], 0, s[4:5]
	s_waitcnt lgkmcnt(0)
	v_mfma_f32_16x16x32_bf16 v[14:17], v[130:133], v[138:141], v[14:17]
	s_add_i32 m0, s21, 0x5000
	v_mfma_f32_16x16x32_bf16 v[10:13], v[130:133], v[142:145], v[10:13]
	global_load_lds_dwordx4 v[214:215], off
	v_mfma_f32_16x16x32_bf16 v[6:9], v[130:133], v[146:149], v[6:9]
	v_mfma_f32_16x16x32_bf16 v[2:5], v[130:133], v[150:153], v[2:5]
	s_setprio 0
	s_branch .Lgt_tail_6
;     ...
;   for (int kt = 0; kt < nk; ++kt) {
;     if (NST == 4 && kt + 2 < nk) asm volatile("s_waitcnt vmcnt(%0)" ::"n"(2 * NLD) : "memory");
;     else if (kt + 1 < nk) asm volatile("s_waitcnt vmcnt(%0)" ::"n"(NLD) : "memory");
;     else asm volatile("s_waitcnt vmcnt(0)" ::: "memory");
;     __builtin_amdgcn_s_barrier();
;     const char* st = smem + (kt % NST) * STAGE;
;     bf16x8 af[MS], bfr[4];
; #pragma unroll
;     for (int ms = 0; ms < MS; ++ms) af[ms] = *(const bf16x8*)(st + aoff_r + ms * 1024);
; #pragma unroll
;     for (int ns = 0; ns < 4; ++ns) bfr[ns] = *(const bf16x8*)(st + boff_r + ns * 1024);
;     asm volatile("" ::: "memory");
;     if (kt + NST - 1 < nk) ISSUE(kt + NST - 1)
;     __builtin_amdgcn_s_setprio(1);
; #pragma unroll
;     for (int ms = 0; ms < MS; ++ms)
; #pragma unroll
;       for (int ns = 0; ns < 4; ++ns) acc[ms][ns] = __builtin_amdgcn_mfma_f32_16x16x32_bf16(af[ms], bfr[ns], acc[ms][ns], 0, 0, 0);
;     __builtin_amdgcn_s_setprio(0);
; template <int MS>
; DEV void zero_acc(f32x4 (&acc)[MS][4]) {
; #pragma unroll
;   for (int a = 0; a < MS; ++a)
; #pragma unroll
;     for (int b = 0; b < 4; ++b) acc[a][b] = f32x4{0.f, 0.f, 0.f, 0.f};
.Lk0_f1:
	s_mul_hi_u32 s10, s20, 0xaaaaaaab
	s_lshr_b32 s10, s10, 1
	s_mul_i32 s10, s10, 0x12000
	v_subrev_u32_e32 v130, s10, v187
	v_add_u32_e32 v139, s19, v189
	v_add_u32_e32 v130, v139, v130
	v_subrev_u32_e32 v138, s10, v238
	v_add_u32_e32 v150, v139, v138
	s_barrier
	ds_read_b128 v[138:141], v150 offset:16384
	ds_read_b128 v[142:145], v150 offset:17408
	ds_read_b128 v[146:149], v150 offset:18432
	ds_read_b128 v[150:153], v150 offset:19456
	ds_read_b128 v[174:177], v130
	ds_read_b128 v[170:173], v130 offset:1024
	ds_read_b128 v[166:169], v130 offset:2048
	ds_read_b128 v[162:165], v130 offset:3072
	ds_read_b128 v[158:161], v130 offset:4096
	ds_read_b128 v[154:157], v130 offset:5120
	ds_read_b128 v[134:137], v130 offset:6144
	ds_read_b128 v[130:133], v130 offset:7168
	s_cmp_gt_u32 s2, 29
	s_cbranch_scc1 .LBB0_209
	s_mul_i32 s11, s15, 0xab
	s_bfe_u32 s11, s11, 0x70009
	s_mul_i32 s11, s11, 3
	s_add_i32 s2, s4, 0x4000
	s_sub_i32 s11, s15, s11
	s_and_b32 s2, s2, 0x7c000
	s_and_b32 s11, s11, 0xff
	s_and_b32 s10, s4, 0x2000
	s_mulk_i32 s11, 0x6000
	s_lshl_b32 s2, s2, 1
	s_add_i32 s21, s13, s11
	s_setprio 1
	s_waitcnt lgkmcnt(7)
	v_mfma_f32_16x16x32_bf16 v[126:129], v[174:177], v[138:141], 0
	v_mfma_f32_16x16x32_bf16 v[122:125], v[174:177], v[142:145], 0
	v_mfma_f32_16x16x32_bf16 v[118:121], v[174:177], v[146:149], 0
	v_mfma_f32_16x16x32_bf16 v[114:117], v[174:177], v[150:153], 0
	v_lshl_add_u64 v[214:215], v[198:199], 0, s[2:3]
	s_waitcnt lgkmcnt(6)
	v_mfma_f32_16x16x32_bf16 v[110:113], v[170:173], v[138:141], 0
	s_lshl_b32 s10, s10, 1
	v_mfma_f32_16x16x32_bf16 v[106:109], v[170:173], v[142:145], 0
	s_mov_b32 s11, s3
	v_mfma_f32_16x16x32_bf16 v[102:105], v[170:173], v[146:149], 0
	v_lshl_add_u64 v[214:215], v[214:215], 0, s[10:11]
	v_mfma_f32_16x16x32_bf16 v[98:101], v[170:173], v[150:153], 0
	s_mov_b32 m0, s21
	s_waitcnt lgkmcnt(5)
	v_mfma_f32_16x16x32_bf16 v[94:97], v[166:169], v[138:141], 0
	global_load_lds_dwordx4 v[214:215], off
	v_mfma_f32_16x16x32_bf16 v[90:93], v[166:169], v[142:145], 0
	v_mfma_f32_16x16x32_bf16 v[86:89], v[166:169], v[146:149], 0
	v_lshl_add_u64 v[214:215], v[200:201], 0, s[2:3]
	v_mfma_f32_16x16x32_bf16 v[82:85], v[166:169], v[150:153], 0
	v_lshl_add_u64 v[214:215], v[214:215], 0, s[10:11]
	s_waitcnt lgkmcnt(4)
	v_mfma_f32_16x16x32_bf16 v[78:81], v[162:165], v[138:141], 0
	s_add_i32 m0, s21, 0x1000
	v_mfma_f32_16x16x32_bf16 v[74:77], v[162:165], v[142:145], 0
	global_load_lds_dwordx4 v[214:215], off
	v_mfma_f32_16x16x32_bf16 v[70:73], v[162:165], v[146:149], 0
	v_lshl_add_u64 v[214:215], v[202:203], 0, s[2:3]
	v_mfma_f32_16x16x32_bf16 v[66:69], v[162:165], v[150:153], 0
	v_lshl_add_u64 v[214:215], v[214:215], 0, s[10:11]
	s_waitcnt lgkmcnt(3)
	v_mfma_f32_16x16x32_bf16 v[62:65], v[158:161], v[138:141], 0
	v_mfma_f32_16x16x32_bf16 v[58:61], v[158:161], v[142:145], 0
	s_add_i32 m0, s21, 0x2000
	v_mfma_f32_16x16x32_bf16 v[54:57], v[158:161], v[146:149], 0
	global_load_lds_dwordx4 v[214:215], off
	v_mfma_f32_16x16x32_bf16 v[50:53], v[158:161], v[150:153], 0
	v_lshl_add_u64 v[214:215], v[204:205], 0, s[2:3]
	s_waitcnt lgkmcnt(2)
	v_mfma_f32_16x16x32_bf16 v[46:49], v[154:157], v[138:141], 0
	v_lshl_add_u64 v[214:215], v[214:215], 0, s[10:11]
	v_mfma_f32_16x16x32_bf16 v[42:45], v[154:157], v[142:145], 0
	s_add_i32 m0, s21, 0x3000
	v_mfma_f32_16x16x32_bf16 v[38:41], v[154:157], v[146:149], 0
	global_load_lds_dwordx4 v[214:215], off
	v_mfma_f32_16x16x32_bf16 v[34:37], v[154:157], v[150:153], 0
	s_waitcnt lgkmcnt(1)
	v_mfma_f32_16x16x32_bf16 v[30:33], v[134:137], v[138:141], 0
	v_lshl_add_u64 v[214:215], v[208:209], 0, s[4:5]
	v_mfma_f32_16x16x32_bf16 v[26:29], v[134:137], v[142:145], 0
	s_add_i32 m0, s21, 0x4000
	v_mfma_f32_16x16x32_bf16 v[22:25], v[134:137], v[146:149], 0
	global_load_lds_dwordx4 v[214:215], off
	v_mfma_f32_16x16x32_bf16 v[18:21], v[134:137], v[150:153], 0
	v_lshl_add_u64 v[214:215], v[206:207], 0, s[4:5]
	s_waitcnt lgkmcnt(0)
	v_mfma_f32_16x16x32_bf16 v[14:17], v[130:133], v[138:141], 0
	s_add_i32 m0, s21, 0x5000
	v_mfma_f32_16x16x32_bf16 v[10:13], v[130:133], v[142:145], 0
	global_load_lds_dwordx4 v[214:215], off
	v_mfma_f32_16x16x32_bf16 v[6:9], v[130:133], v[146:149], 0
	v_mfma_f32_16x16x32_bf16 v[2:5], v[130:133], v[150:153], 0
	s_setprio 0
	s_branch .Lgt_tail_6

;     ...
;   const int rg = (l15 >> 2) & 3;
;   const int gr = (rg == 0) ? 0 : (rg == 1) ? 2 : (rg == 2) ? 3 : 1;
;   const int aoff_r = (wm * (MS * 16) + l15) * 64 + ((quad ^ gr) << 4);
;   const int boff_r = A_BYTES + (wn * 64 + l15) * 64 + ((quad ^ gr) << 4);
; template <int MS>
; DEV void zero_acc(f32x4 (&acc)[MS][4]) {
; #pragma unroll
;   for (int a = 0; a < MS; ++a)
; #pragma unroll
;     for (int b = 0; b < 4; ++b) acc[a][b] = f32x4{0.f, 0.f, 0.f, 0.f};
.LBB0_2335:
	s_mov_b64 s[4:5], 0x4000
	v_lshlrev_b32_e32 v6, 6, v9
	v_lshl_add_u64 v[208:209], v[2:3], 0, s[4:5]
	v_and_b32_e32 v178, 0xffffe3c0, v6
	v_bitop3_b32 v187, v10, v9, 48 bitop3:0x78
	v_and_b32_e32 v189, 0x13c0, v6
	v_lshl_add_u64 v[206:207], v[4:5], 0, s[4:5]
	s_mov_b64 s[4:5], 0
	s_mov_b32 s13, 2
	s_mov_b32 s15, 0
	s_mov_b32 s16, 0
	s_branch .LBB0_2337

;     ...
;   for (int kt = 0; kt < nk; ++kt) {
;     if (NST == 4 && kt + 2 < nk) asm volatile("s_waitcnt vmcnt(%0)" ::"n"(2 * NLD) : "memory");
;     else if (kt + 1 < nk) asm volatile("s_waitcnt vmcnt(%0)" ::"n"(NLD) : "memory");
;     else asm volatile("s_waitcnt vmcnt(0)" ::: "memory");
;     __builtin_amdgcn_s_barrier();
;     const char* st = smem + (kt % NST) * STAGE;
;     bf16x8 af[MS], bfr[4];
; #pragma unroll
;     for (int ms = 0; ms < MS; ++ms) af[ms] = *(const bf16x8*)(st + aoff_r + ms * 1024);
; #pragma unroll
;     for (int ns = 0; ns < 4; ++ns) bfr[ns] = *(const bf16x8*)(st + boff_r + ns * 1024);
;     asm volatile("" ::: "memory");
;     if (kt + NST - 1 < nk) ISSUE(kt + NST - 1)
;     __builtin_amdgcn_s_setprio(1);
; #pragma unroll
;     for (int ms = 0; ms < MS; ++ms)
; #pragma unroll
;       for (int ns = 0; ns < 4; ++ns) acc[ms][ns] = __builtin_amdgcn_mfma_f32_16x16x32_bf16(af[ms], bfr[ns], acc[ms][ns], 0, 0, 0);
;     __builtin_amdgcn_s_setprio(0);
.LBB0_2341:
	s_cmp_eq_u32 s2, 0
	s_cbranch_scc1 .Lk0_f2
	s_mul_hi_u32 s8, s16, 0xaaaaaaab
	s_lshr_b32 s8, s8, 1
	s_mul_i32 s8, s8, 0x12000
	v_subrev_u32_e32 v130, s8, v178
	v_add_u32_e32 v139, s15, v187
	v_add_u32_e32 v130, v139, v130
	v_subrev_u32_e32 v138, s8, v189
	v_add_u32_e32 v150, v139, v138
	s_barrier
	ds_read_b128 v[138:141], v150 offset:16384
	ds_read_b128 v[142:145], v150 offset:17408
	ds_read_b128 v[146:149], v150 offset:18432
	ds_read_b128 v[150:153], v150 offset:19456
	ds_read_b128 v[174:177], v130
	ds_read_b128 v[170:173], v130 offset:1024
	ds_read_b128 v[166:169], v130 offset:2048
	ds_read_b128 v[162:165], v130 offset:3072
	ds_read_b128 v[158:161], v130 offset:4096
	ds_read_b128 v[154:157], v130 offset:5120
	ds_read_b128 v[134:137], v130 offset:6144
	ds_read_b128 v[130:133], v130 offset:7168
	s_cmp_gt_u32 s2, 29
	s_cbranch_scc1 .LBB0_2336
	s_mul_i32 s9, s13, 0xab
	s_bfe_u32 s9, s9, 0x70009
	s_mul_i32 s9, s9, 3
	s_add_i32 s2, s4, 0x4000
	s_sub_i32 s9, s13, s9
	s_and_b32 s2, s2, 0x7c000
	s_and_b32 s9, s9, 0xff
	s_and_b32 s8, s4, 0x2000
	s_mulk_i32 s9, 0x6000
	s_lshl_b32 s2, s2, 1
	s_add_i32 s17, s11, s9
	s_setprio 1
	s_waitcnt lgkmcnt(7)
	v_mfma_f32_16x16x32_bf16 v[126:129], v[174:177], v[138:141], v[126:129]
	v_mfma_f32_16x16x32_bf16 v[122:125], v[174:177], v[142:145], v[122:125]
	v_mfma_f32_16x16x32_bf16 v[118:121], v[174:177], v[146:149], v[118:121]
	v_mfma_f32_16x16x32_bf16 v[114:117], v[174:177], v[150:153], v[114:117]
	v_lshl_add_u64 v[236:237], v[198:199], 0, s[2:3]
	s_waitcnt lgkmcnt(6)
	v_mfma_f32_16x16x32_bf16 v[110:113], v[170:173], v[138:141], v[110:113]
	s_lshl_b32 s8, s8, 1
	v_mfma_f32_16x16x32_bf16 v[106:109], v[170:173], v[142:145], v[106:109]
	s_mov_b32 s9, s3
	v_mfma_f32_16x16x32_bf16 v[102:105], v[170:173], v[146:149], v[102:105]
	v_lshl_add_u64 v[236:237], v[236:237], 0, s[8:9]
	v_mfma_f32_16x16x32_bf16 v[98:101], v[170:173], v[150:153], v[98:101]
	s_mov_b32 m0, s17
	s_waitcnt lgkmcnt(5)
	v_mfma_f32_16x16x32_bf16 v[94:97], v[166:169], v[138:141], v[94:97]
	global_load_lds_dwordx4 v[236:237], off
	v_mfma_f32_16x16x32_bf16 v[90:93], v[166:169], v[142:145], v[90:93]
	v_mfma_f32_16x16x32_bf16 v[86:89], v[166:169], v[146:149], v[86:89]
	v_lshl_add_u64 v[236:237], v[200:201], 0, s[2:3]
	v_mfma_f32_16x16x32_bf16 v[82:85], v[166:169], v[150:153], v[82:85]
	v_lshl_add_u64 v[236:237], v[236:237], 0, s[8:9]
	s_waitcnt lgkmcnt(4)
	v_mfma_f32_16x16x32_bf16 v[78:81], v[162:165], v[138:141], v[78:81]
	s_add_i32 m0, s17, 0x1000
	v_mfma_f32_16x16x32_bf16 v[74:77], v[162:165], v[142:145], v[74:77]
	global_load_lds_dwordx4 v[236:237], off
	v_mfma_f32_16x16x32_bf16 v[70:73], v[162:165], v[146:149], v[70:73]
	v_lshl_add_u64 v[236:237], v[202:203], 0, s[2:3]
	v_mfma_f32_16x16x32_bf16 v[66:69], v[162:165], v[150:153], v[66:69]
	v_lshl_add_u64 v[236:237], v[236:237], 0, s[8:9]
	s_waitcnt lgkmcnt(3)
	v_mfma_f32_16x16x32_bf16 v[62:65], v[158:161], v[138:141], v[62:65]
	v_mfma_f32_16x16x32_bf16 v[58:61], v[158:161], v[142:145], v[58:61]
	s_add_i32 m0, s17, 0x2000
	v_mfma_f32_16x16x32_bf16 v[54:57], v[158:161], v[146:149], v[54:57]
	global_load_lds_dwordx4 v[236:237], off
	v_mfma_f32_16x16x32_bf16 v[50:53], v[158:161], v[150:153], v[50:53]
	v_lshl_add_u64 v[236:237], v[204:205], 0, s[2:3]
	s_waitcnt lgkmcnt(2)
	v_mfma_f32_16x16x32_bf16 v[46:49], v[154:157], v[138:141], v[46:49]
	v_lshl_add_u64 v[236:237], v[236:237], 0, s[8:9]
	v_mfma_f32_16x16x32_bf16 v[42:45], v[154:157], v[142:145], v[42:45]
	s_add_i32 m0, s17, 0x3000
	v_mfma_f32_16x16x32_bf16 v[38:41], v[154:157], v[146:149], v[38:41]
	global_load_lds_dwordx4 v[236:237], off
	v_mfma_f32_16x16x32_bf16 v[34:37], v[154:157], v[150:153], v[34:37]
	s_waitcnt lgkmcnt(1)
	v_mfma_f32_16x16x32_bf16 v[30:33], v[134:137], v[138:141], v[30:33]
	v_lshl_add_u64 v[236:237], v[208:209], 0, s[4:5]
	v_mfma_f32_16x16x32_bf16 v[26:29], v[134:137], v[142:145], v[26:29]
	s_add_i32 m0, s17, 0x4000
	v_mfma_f32_16x16x32_bf16 v[22:25], v[134:137], v[146:149], v[22:25]
	global_load_lds_dwordx4 v[236:237], off
	v_mfma_f32_16x16x32_bf16 v[18:21], v[134:137], v[150:153], v[18:21]
	v_lshl_add_u64 v[236:237], v[206:207], 0, s[4:5]
	s_waitcnt lgkmcnt(0)
	v_mfma_f32_16x16x32_bf16 v[14:17], v[130:133], v[138:141], v[14:17]
	s_add_i32 m0, s17, 0x5000
	v_mfma_f32_16x16x32_bf16 v[10:13], v[130:133], v[142:145], v[10:13]
	global_load_lds_dwordx4 v[236:237], off
	v_mfma_f32_16x16x32_bf16 v[6:9], v[130:133], v[146:149], v[6:9]
	v_mfma_f32_16x16x32_bf16 v[2:5], v[130:133], v[150:153], v[2:5]
	s_setprio 0
	s_branch .Lgt_tail_16
;     ...
;   for (int kt = 0; kt < nk; ++kt) {
;     if (NST == 4 && kt + 2 < nk) asm volatile("s_waitcnt vmcnt(%0)" ::"n"(2 * NLD) : "memory");
;     else if (kt + 1 < nk) asm volatile("s_waitcnt vmcnt(%0)" ::"n"(NLD) : "memory");
;     else asm volatile("s_waitcnt vmcnt(0)" ::: "memory");
;     __builtin_amdgcn_s_barrier();
;     const char* st = smem + (kt % NST) * STAGE;
;     bf16x8 af[MS], bfr[4];
; #pragma unroll
;     for (int ms = 0; ms < MS; ++ms) af[ms] = *(const bf16x8*)(st + aoff_r + ms * 1024);
; #pragma unroll
;     for (int ns = 0; ns < 4; ++ns) bfr[ns] = *(const bf16x8*)(st + boff_r + ns * 1024);
;     asm volatile("" ::: "memory");
;     if (kt + NST - 1 < nk) ISSUE(kt + NST - 1)
;     __builtin_amdgcn_s_setprio(1);
; #pragma unroll
;     for (int ms = 0; ms < MS; ++ms)
; #pragma unroll
;       for (int ns = 0; ns < 4; ++ns) acc[ms][ns] = __builtin_amdgcn_mfma_f32_16x16x32_bf16(af[ms], bfr[ns], acc[ms][ns], 0, 0, 0);
;     __builtin_amdgcn_s_setprio(0);
; template <int MS>
; DEV void zero_acc(f32x4 (&acc)[MS][4]) {
; #pragma unroll
;   for (int a = 0; a < MS; ++a)
; #pragma unroll
;     for (int b = 0; b < 4; ++b) acc[a][b] = f32x4{0.f, 0.f, 0.f, 0.f};
.Lk0_f2:
	s_mul_hi_u32 s8, s16, 0xaaaaaaab
	s_lshr_b32 s8, s8, 1
	s_mul_i32 s8, s8, 0x12000
	v_subrev_u32_e32 v130, s8, v178
	v_add_u32_e32 v139, s15, v187
	v_add_u32_e32 v130, v139, v130
	v_subrev_u32_e32 v138, s8, v189
	v_add_u32_e32 v150, v139, v138
	s_barrier
	ds_read_b128 v[138:141], v150 offset:16384
	ds_read_b128 v[142:145], v150 offset:17408
	ds_read_b128 v[146:149], v150 offset:18432
	ds_read_b128 v[150:153], v150 offset:19456
	ds_read_b128 v[174:177], v130
	ds_read_b128 v[170:173], v130 offset:1024
	ds_read_b128 v[166:169], v130 offset:2048
	ds_read_b128 v[162:165], v130 offset:3072
	ds_read_b128 v[158:161], v130 offset:4096
	ds_read_b128 v[154:157], v130 offset:5120
	ds_read_b128 v[134:137], v130 offset:6144
	ds_read_b128 v[130:133], v130 offset:7168
	s_cmp_gt_u32 s2, 29
	s_cbranch_scc1 .LBB0_2336
	s_mul_i32 s9, s13, 0xab
	s_bfe_u32 s9, s9, 0x70009
	s_mul_i32 s9, s9, 3
	s_add_i32 s2, s4, 0x4000
	s_sub_i32 s9, s13, s9
	s_and_b32 s2, s2, 0x7c000
	s_and_b32 s9, s9, 0xff
	s_and_b32 s8, s4, 0x2000
	s_mulk_i32 s9, 0x6000
	s_lshl_b32 s2, s2, 1
	s_add_i32 s17, s11, s9
	s_setprio 1
	s_waitcnt lgkmcnt(7)
	v_mfma_f32_16x16x32_bf16 v[126:129], v[174:177], v[138:141], 0
	v_mfma_f32_16x16x32_bf16 v[122:125], v[174:177], v[142:145], 0
	v_mfma_f32_16x16x32_bf16 v[118:121], v[174:177], v[146:149], 0
	v_mfma_f32_16x16x32_bf16 v[114:117], v[174:177], v[150:153], 0
	v_lshl_add_u64 v[236:237], v[198:199], 0, s[2:3]
	s_waitcnt lgkmcnt(6)
	v_mfma_f32_16x16x32_bf16 v[110:113], v[170:173], v[138:141], 0
	s_lshl_b32 s8, s8, 1
	v_mfma_f32_16x16x32_bf16 v[106:109], v[170:173], v[142:145], 0
	s_mov_b32 s9, s3
	v_mfma_f32_16x16x32_bf16 v[102:105], v[170:173], v[146:149], 0
	v_lshl_add_u64 v[236:237], v[236:237], 0, s[8:9]
	v_mfma_f32_16x16x32_bf16 v[98:101], v[170:173], v[150:153], 0
	s_mov_b32 m0, s17
	s_waitcnt lgkmcnt(5)
	v_mfma_f32_16x16x32_bf16 v[94:97], v[166:169], v[138:141], 0
	global_load_lds_dwordx4 v[236:237], off
	v_mfma_f32_16x16x32_bf16 v[90:93], v[166:169], v[142:145], 0
	v_mfma_f32_16x16x32_bf16 v[86:89], v[166:169], v[146:149], 0
	v_lshl_add_u64 v[236:237], v[200:201], 0, s[2:3]
	v_mfma_f32_16x16x32_bf16 v[82:85], v[166:169], v[150:153], 0
	v_lshl_add_u64 v[236:237], v[236:237], 0, s[8:9]
	s_waitcnt lgkmcnt(4)
	v_mfma_f32_16x16x32_bf16 v[78:81], v[162:165], v[138:141], 0
	s_add_i32 m0, s17, 0x1000
	v_mfma_f32_16x16x32_bf16 v[74:77], v[162:165], v[142:145], 0
	global_load_lds_dwordx4 v[236:237], off
	v_mfma_f32_16x16x32_bf16 v[70:73], v[162:165], v[146:149], 0
	v_lshl_add_u64 v[236:237], v[202:203], 0, s[2:3]
	v_mfma_f32_16x16x32_bf16 v[66:69], v[162:165], v[150:153], 0
	v_lshl_add_u64 v[236:237], v[236:237], 0, s[8:9]
	s_waitcnt lgkmcnt(3)
	v_mfma_f32_16x16x32_bf16 v[62:65], v[158:161], v[138:141], 0
	v_mfma_f32_16x16x32_bf16 v[58:61], v[158:161], v[142:145], 0
	s_add_i32 m0, s17, 0x2000
	v_mfma_f32_16x16x32_bf16 v[54:57], v[158:161], v[146:149], 0
	global_load_lds_dwordx4 v[236:237], off
	v_mfma_f32_16x16x32_bf16 v[50:53], v[158:161], v[150:153], 0
	v_lshl_add_u64 v[236:237], v[204:205], 0, s[2:3]
	s_waitcnt lgkmcnt(2)
	v_mfma_f32_16x16x32_bf16 v[46:49], v[154:157], v[138:141], 0
	v_lshl_add_u64 v[236:237], v[236:237], 0, s[8:9]
	v_mfma_f32_16x16x32_bf16 v[42:45], v[154:157], v[142:145], 0
	s_add_i32 m0, s17, 0x3000
	v_mfma_f32_16x16x32_bf16 v[38:41], v[154:157], v[146:149], 0
	global_load_lds_dwordx4 v[236:237], off
	v_mfma_f32_16x16x32_bf16 v[34:37], v[154:157], v[150:153], 0
	s_waitcnt lgkmcnt(1)
	v_mfma_f32_16x16x32_bf16 v[30:33], v[134:137], v[138:141], 0
	v_lshl_add_u64 v[236:237], v[208:209], 0, s[4:5]
	v_mfma_f32_16x16x32_bf16 v[26:29], v[134:137], v[142:145], 0
	s_add_i32 m0, s17, 0x4000
	v_mfma_f32_16x16x32_bf16 v[22:25], v[134:137], v[146:149], 0
	global_load_lds_dwordx4 v[236:237], off
	v_mfma_f32_16x16x32_bf16 v[18:21], v[134:137], v[150:153], 0
	v_lshl_add_u64 v[236:237], v[206:207], 0, s[4:5]
	s_waitcnt lgkmcnt(0)
	v_mfma_f32_16x16x32_bf16 v[14:17], v[130:133], v[138:141], 0
	s_add_i32 m0, s17, 0x5000
	v_mfma_f32_16x16x32_bf16 v[10:13], v[130:133], v[142:145], 0
	global_load_lds_dwordx4 v[236:237], off
	v_mfma_f32_16x16x32_bf16 v[6:9], v[130:133], v[146:149], 0
	v_mfma_f32_16x16x32_bf16 v[2:5], v[130:133], v[150:153], 0
	s_setprio 0
	s_branch .Lgt_tail_16
